# mixer: dropped the two phase-internal L2 invalidates (buffer_inv sc1 after the late-tile / scan counters): those lines are never read on the XCD before the counters are satisfied, so no stale copies c
# speedup vs baseline: 1.0168x; 1.0157x over previous
.LBB0_338:
	s_or_b64 exec, exec, s[18:19]
	s_mov_b64 s[30:31], -1
	s_barrier
	s_waitcnt vmcnt(0)
.LBB0_339:
	v_mov_b32_e32 v41, v181
	s_mul_i32 s36, s1, 48
	v_readfirstlane_b32 s5, v41
	s_ashr_i32 s22, s5, 6
	v_and_b32_e32 v43, 15, v41
	s_waitcnt vmcnt(0)
	v_lshlrev_b32_e32 v2, 2, v41
	s_ashr_i32 s37, s5, 7
	s_lshl_b32 s5, s22, 9
	v_and_b32_e32 v12, 48, v41
	v_lshlrev_b32_e32 v13, 6, v43
	v_and_b32_e32 v14, 32, v2
	s_and_b32 s55, s5, 0x400
	s_lshl_b32 s5, s22, 3
	v_bitop3_b32 v3, v13, v14, v12 bitop3:0x36
	v_ashrrev_i32_e32 v16, 4, v41
	v_ashrrev_i32_e32 v100, 3, v41
	v_lshlrev_b32_e32 v19, 3, v41
	v_and_or_b32 v12, s5, 8, v12
	s_lshl_b32 s5, s22, 4
	v_bfe_u32 v0, v41, 4, 2
	v_lshlrev_b32_e32 v17, 6, v16
	v_lshlrev_b32_e32 v18, 5, v100
	v_and_b32_e32 v19, 24, v19
	v_bitop3_b32 v56, v12, v14, v13 bitop3:0x36
	v_mov_b32_e32 v12, s5
	s_movk_i32 s5, 0x210
	v_and_b32_e32 v58, 7, v41
	s_add_i32 s3, s36, s27
	v_lshlrev_b32_e32 v45, 2, v0
	v_lshrrev_b32_e32 v2, 4, v41
	v_bfe_u32 v15, v41, 2, 1
	v_and_b32_e32 v17, 64, v17
	v_and_or_b32 v40, v18, 32, v19
	v_lshlrev_b32_e32 v18, 1, v16
	v_mad_u32_u24 v0, v0, s5, v12
	v_lshlrev_b32_e32 v102, 4, v58
	s_movk_i32 s5, 0x84
	v_and_or_b32 v2, v2, 30, v15
	v_or_b32_e32 v42, v40, v17
	v_and_or_b32 v49, v18, 62, v15
	v_lshlrev_b32_e32 v50, 7, v17
	v_lshrrev_b32_e32 v15, 7, v41
	v_and_b32_e32 v17, 1, v100
	v_mad_u64_u32 v[46:47], s[18:19], v100, s5, v[102:103]
	s_mul_i32 s23, s3, 0xf83f
	v_lshrrev_b32_e32 v48, 2, v41
	v_and_or_b32 v15, v15, 2, v17
	v_lshlrev_b32_e32 v18, 6, v2
	s_lshr_b32 s18, s23, 21
	v_and_b32_e32 v18, 0x3c0, v18
	v_lshlrev_b32_e32 v19, 1, v19
	v_lshlrev_b32_e32 v51, 10, v15
	v_and_b32_e32 v15, 32, v48
	s_mulk_i32 s18, 0xffdf
	v_bitop3_b32 v52, v18, v15, v19 bitop3:0x36
	v_lshrrev_b32_e32 v15, 2, v16
	s_add_i32 s18, s18, s3
	v_and_or_b32 v15, v15, 6, v17
	v_lshlrev_b32_e32 v17, 6, v49
	s_movk_i32 s11, 0x3c0
	s_and_b32 s38, s22, 3
	s_and_b32 s39, s37, -2
	s_lshr_b32 s42, s23, 24
	s_lshl_b32 s18, s18, 6
	v_and_or_b32 v53, v17, s11, v19
	s_lshl_b32 s11, s38, 11
	s_lshl_b32 s33, s39, 11
	s_lshl_b32 s59, s22, 11
	s_add_i32 s5, s3, 48
	s_mul_i32 s40, s42, 0x840
	s_ashr_i32 s19, s18, 31
	s_add_u32 s40, s40, s18
	s_addc_u32 s41, 0, s19
	v_or_b32_e32 v12, s40, v2
	v_mov_b32_e32 v13, s41
	s_lshr_b32 s23, s23, 14
	v_lshlrev_b64 v[12:13], 14, v[12:13]
	s_and_b32 s23, s23, 0x380
	v_lshl_add_u64 v[12:13], v[8:9], 0, v[12:13]
	s_lshl_b32 s52, s23, 1
	s_mul_i32 s60, s42, 0xc00
	v_or_b32_e32 v57, v0, v43
	v_lshl_add_u64 v[12:13], v[12:13], 0, s[52:53]
	v_lshlrev_b32_e32 v0, 1, v42
	s_or_b32 s42, s60, s23
	v_lshlrev_b32_e32 v54, 10, v15
	v_lshlrev_b32_e32 v15, 3, v16
	v_lshl_add_u64 v[16:17], v[12:13], 0, v[0:1]
	v_add_u32_e32 v0, s42, v100
	s_addk_i32 s60, 0x400
	v_mad_i64_i32 v[12:13], s[42:43], v0, s80, v[10:11]
	s_lshl_b64 s[18:19], s[18:19], 1
	v_or_b32_e32 v0, s60, v49
	v_lshl_add_u64 v[12:13], v[12:13], 0, s[18:19]
	v_mov_b32_e32 v103, v1
	v_or_b32_e32 v0, s23, v0
	v_lshl_add_u64 v[20:21], v[12:13], 0, v[102:103]
	v_mad_u64_u32 v[12:13], s[42:43], v0, s80, v[10:11]
	v_lshl_add_u64 v[12:13], v[12:13], 0, s[18:19]
	s_lshl_b32 s18, s3, 3
	s_ashr_i32 s23, s22, 31
	s_add_u32 s18, s22, s18
	v_lshlrev_b32_e32 v0, 1, v40
	s_addc_u32 s19, s23, 0
	v_and_b32_e32 v55, 32, v15
	v_lshl_add_u64 v[28:29], v[12:13], 0, v[0:1]
	global_load_dwordx4 v[12:15], v[16:17], off
	v_add_co_u32_e32 v16, vcc, s15, v16
	s_lshl_b64 s[18:19], s[18:19], 12
	v_ashrrev_i32_e32 v101, 31, v100
	v_addc_co_u32_e32 v17, vcc, 0, v17, vcc
	v_lshl_add_u64 v[36:37], v[6:7], 0, s[18:19]
	v_add_co_u32_e32 v30, vcc, s14, v20
	v_readfirstlane_b32 s18, v36
	v_readfirstlane_b32 s19, v37
	v_lshl_add_u64 v[36:37], s[40:41], 0, v[100:101]
	v_addc_co_u32_e32 v31, vcc, 0, v21, vcc
	v_lshlrev_b64 v[36:37], 14, v[36:37]
	v_and_b32_e32 v38, 63, v41
	v_add_co_u32_e32 v32, vcc, s14, v28
	v_lshl_add_u64 v[36:37], v[8:9], 0, v[36:37]
	s_nop 0
	v_addc_co_u32_e32 v33, vcc, 0, v29, vcc
	v_lshlrev_b32_e32 v0, 4, v38
	v_lshl_add_u64 v[36:37], v[36:37], 0, s[52:53]
	v_lshlrev_b32_e32 v38, 5, v58
	v_mov_b32_e32 v39, v1
	global_load_dwordx4 v[16:19], v[16:17], off
	s_nop 0
	global_load_dwordx4 v[20:23], v[20:21], off
	s_nop 0
	global_load_dwordx4 v[24:27], v[28:29], off
	s_nop 0
	global_load_dwordx4 v[28:31], v[30:31], off
	s_nop 0
	global_load_dwordx4 v[32:35], v[32:33], off
	s_nop 0
	global_load_dwordx4 v[80:83], v0, s[18:19]
	global_load_dwordx4 v[76:79], v0, s[18:19] offset:1024
	global_load_dwordx4 v[72:75], v0, s[18:19] offset:2048
	global_load_dwordx4 v[68:71], v0, s[18:19] offset:3072
	v_lshl_add_u64 v[36:37], v[36:37], 0, v[38:39]
	s_movk_i32 s18, 0x1000
	v_lshl_add_u64 v[38:39], v[36:37], 0, s[12:13]
	v_add_co_u32_e32 v36, vcc, s18, v36
	v_lshl_add_u32 v46, v46, 2, 0
	s_nop 0
	v_addc_co_u32_e32 v37, vcc, 0, v37, vcc
	global_load_dwordx4 v[64:67], v[36:37], off offset:2048
	s_nop 0
	global_load_dwordx4 v[36:39], v[38:39], off offset:16
	v_and_b32_e32 v62, 64, v205
	v_add_u32_e32 v120, 0x12000, v46
	v_add_u32_e32 v121, 0x12010, v46
	v_add_u32_e32 v122, 0x12020, v46
	v_add_u32_e32 v123, 0x12030, v46
	v_xor_b32_e32 v46, 1, v205
	v_add_u32_e32 v62, 64, v62
	v_cmp_lt_i32_e32 vcc, v46, v62
	v_and_b32_e32 v47, 24, v48
	v_lshrrev_b32_e32 v48, 2, v100
	v_cndmask_b32_e32 v46, v205, v46, vcc
	v_lshlrev_b32_e32 v124, 2, v46
	v_xor_b32_e32 v46, 2, v205
	v_cmp_lt_i32_e32 vcc, v46, v62
	v_add3_u32 v50, 0, v50, v52
	v_and_b32_e32 v48, 4, v48
	v_cndmask_b32_e32 v46, v205, v46, vcc
	v_lshlrev_b32_e32 v125, 2, v46
	v_xor_b32_e32 v46, 4, v205
	v_and_b32_e32 v52, 3, v100
	v_cmp_lt_i32_e32 vcc, v46, v62
	v_or3_b32 v47, v52, v48, v47
	v_lshlrev_b32_e32 v48, 7, v100
	v_cndmask_b32_e32 v46, v205, v46, vcc
	v_lshlrev_b32_e32 v59, 4, v41
	v_lshlrev_b32_e32 v126, 2, v46
	v_and_b32_e32 v46, 0xffffe000, v48
	v_and_b32_e32 v48, 4, v41
	v_lshlrev_b32_e32 v41, 8, v41
	v_and_b32_e32 v41, 0x300, v41
	s_lshl_b32 s18, s38, 4
	v_lshl_or_b32 v41, v47, 1, v41
	v_lshrrev_b32_e32 v52, 5, v100
	v_and_b32_e32 v59, 32, v59
	v_or_b32_e32 v104, 0x400, v49
	v_or_b32_e32 v49, s18, v45
	v_add_u32_e32 v46, 0, v46
	v_or_b32_e32 v47, 64, v41
	v_sub_u32_e32 v43, v43, v49
	v_and_or_b32 v48, v52, 1, v48
	v_xad_u32 v52, v41, v59, v46
	v_xad_u32 v62, v47, v59, v46
	v_or_b32_e32 v47, 0x80, v41
	v_or_b32_e32 v41, 0xc0, v41
	v_xad_u32 v63, v47, v59, v46
	v_xad_u32 v41, v41, v59, v46
	v_lshl_add_u32 v46, s39, 4, v43
	s_add_i32 s33, s33, 0
	v_cvt_f32_i32_e32 v47, v46
	v_add_u32_e32 v59, -1, v46
	v_add_u32_e32 v84, -2, v46
	v_add_u32_e32 v46, -3, v46
	v_xad_u32 v53, v53, v55, 0
	v_bitop3_b32 v49, s18, 63, v45 bitop3:0x36
	v_bitop3_b32 v55, s18, 62, v45 bitop3:0x36
	v_bitop3_b32 v60, s18, 61, v45 bitop3:0x36
	v_bitop3_b32 v61, s18, 60, v45 bitop3:0x36
	s_add_i32 s18, s33, s55
	v_cvt_f32_i32_e32 v59, v59
	v_cvt_f32_i32_e32 v46, v46
	s_add_i32 s40, s18, 0x10000
	s_lshl_b64 s[18:19], s[22:23], 12
	s_lshl_b32 s22, s37, 4
	s_or_b32 s22, s22, 16
	v_cvt_f32_ubyte0_e32 v49, v49
	v_cvt_f32_ubyte0_e32 v55, v55
	v_cvt_f32_ubyte0_e32 v61, v61
	v_add_u32_e32 v43, s22, v43
	v_sub_f32_e64 v128, |v47|, v49
	v_sub_f32_e64 v129, |v59|, v55
	v_sub_f32_e64 v131, |v46|, v61
	v_cvt_f32_i32_e32 v46, v43
	v_add_u32_e32 v47, -1, v43
	v_add_u32_e32 v59, -2, v43
	v_add_u32_e32 v43, -3, v43
	v_cvt_f32_i32_e32 v43, v43
	v_cvt_f32_i32_e32 v47, v47
	s_add_i32 s52, s24, s36
	s_add_i32 s11, s11, 0
	v_sub_f32_e64 v135, |v43|, v61
	v_or_b32_e32 v43, 1, v45
	v_cvt_f32_ubyte0_e32 v136, v43
	v_or_b32_e32 v43, 2, v45
	v_cvt_f32_ubyte0_e32 v137, v43
	v_or_b32_e32 v43, 3, v45
	v_cvt_f32_ubyte0_e32 v138, v43
	v_add_u32_e32 v43, 4, v45
	v_cvt_f32_ubyte0_e32 v139, v43
	v_or_b32_e32 v43, 17, v45
	v_cvt_f32_ubyte0_e32 v140, v43
	v_or_b32_e32 v43, 18, v45
	v_cvt_f32_ubyte0_e32 v141, v43
	v_or_b32_e32 v43, 19, v45
	v_cvt_f32_ubyte0_e32 v142, v43
	v_add_u32_e32 v43, 20, v45
	v_cvt_f32_ubyte0_e32 v143, v43
	v_or_b32_e32 v43, 33, v45
	v_cvt_f32_ubyte0_e32 v144, v43
	v_or_b32_e32 v43, 34, v45
	v_cvt_f32_ubyte0_e32 v145, v43
	v_or_b32_e32 v43, 35, v45
	v_cvt_f32_ubyte0_e32 v146, v43
	v_add_u32_e32 v43, 36, v45
	s_add_i32 s38, s59, 0
	v_cvt_f32_i32_e32 v84, v84
	v_cvt_f32_i32_e32 v59, v59
	v_cvt_f32_ubyte0_e32 v147, v43
	v_or_b32_e32 v43, 49, v45
	s_lshl_b32 s22, s52, 6
	s_lshl_b64 s[36:37], s[52:53], 15
	v_cvt_f32_ubyte0_e32 v148, v43
	v_or_b32_e32 v43, 50, v45
	s_add_u32 s18, s36, s18
	v_sub_f32_e64 v132, |v46|, v49
	v_sub_f32_e64 v133, |v47|, v55
	v_cvt_f32_ubyte0_e32 v149, v43
	v_or_b32_e32 v43, 51, v45
	v_lshlrev_b32_e32 v46, 6, v58
	v_mov_b32_e32 v47, v1
	s_addc_u32 s19, s37, s19
	v_lshlrev_b32_e32 v44, 3, v58
	v_cvt_f32_ubyte0_e32 v60, v60
	v_lshl_add_u32 v57, v57, 2, 0
	v_lshlrev_b32_e32 v48, 10, v48
	v_cvt_f32_ubyte0_e32 v162, v43
	v_add_u32_e32 v43, 52, v45
	v_lshl_add_u64 v[106:107], v[152:153], 0, v[46:47]
	v_lshl_add_u64 v[46:47], v[6:7], 0, s[18:19]
	v_add_u32_e32 v103, 0x12000, v57
	v_add_u32_e32 v127, 0x18300, v57
	v_sub_f32_e64 v130, |v84|, v60
	v_sub_f32_e64 v134, |v59|, v60
	v_cvt_f32_ubyte0_e32 v163, v43
	v_add_u32_e32 v164, 0x12210, v57
	v_add_u32_e32 v165, 0x12420, v57
	v_add_u32_e32 v166, 0x12630, v57
	v_add_u32_e32 v167, 0x14100, v57
	v_add_u32_e32 v168, 0x14310, v57
	v_add_u32_e32 v169, 0x14520, v57
	v_add_u32_e32 v170, 0x14730, v57
	v_add_u32_e32 v171, 0x16200, v57
	v_add_u32_e32 v172, 0x16410, v57
	v_add_u32_e32 v173, 0x16620, v57
	v_add_u32_e32 v174, 0x16830, v57
	v_add_u32_e32 v175, 0x18510, v57
	v_add_u32_e32 v176, 0x18720, v57
	v_add_u32_e32 v177, 0x18930, v57
	v_lshl_add_u64 v[108:109], v[46:47], 0, v[0:1]
	v_add_u32_e32 v178, v50, v51
	v_add_u32_e32 v179, v52, v48
	v_add_u32_e32 v184, v62, v48
	v_add_u32_e32 v185, v63, v48
	v_add_u32_e32 v186, v41, v48
	v_add_u32_e32 v187, v53, v54
	v_lshlrev_b32_e32 v110, 1, v42
	v_lshlrev_b32_e32 v112, 1, v44
	v_lshlrev_b32_e32 v114, 1, v40
	v_add_u32_e32 v188, s40, v56
	s_waitcnt vmcnt(0)
	v_mov_b64_e32 v[58:59], v[38:39]
	v_mov_b64_e32 v[60:61], v[64:65]
	v_mov_b64_e32 v[40:41], v[68:69]
	v_mov_b64_e32 v[44:45], v[72:73]
	v_mov_b64_e32 v[48:49], v[76:77]
	v_mov_b64_e32 v[52:53], v[80:81]
	v_mov_b32_e32 v105, v1
	s_lshl_b32 s18, s3, 6
	s_mov_b32 s19, s52
	v_mov_b64_e32 v[56:57], v[36:37]
	v_mov_b64_e32 v[62:63], v[66:67]
	v_mov_b64_e32 v[42:43], v[70:71]
	v_mov_b64_e32 v[46:47], v[74:75]
	v_mov_b64_e32 v[50:51], v[78:79]
	v_mov_b64_e32 v[54:55], v[82:83]
	s_branch .LBB0_341

.LBB0_397:
	s_or_b64 exec, exec, s[18:19]
	s_waitcnt lgkmcnt(0)
	s_barrier
.LBB0_398:
	s_cmp_eq_u32 s3, 0
	s_cselect_b64 s[18:19], -1, 0
	s_and_b64 s[18:19], s[18:19], s[30:31]
	v_cndmask_b32_e64 v0, 0, 1, s[18:19]
	v_cmp_ne_u32_e64 s[40:41], 1, v0
	s_andn2_b64 vcc, exec, s[18:19]
	v_lshl_add_u64 v[122:123], s[44:45], 0, v[164:165]
	s_cbranch_vccnz .LBB0_400
	v_lshlrev_b64 v[2:3], 14, v[122:123]
	v_lshl_add_u64 v[76:77], v[8:9], 0, v[2:3]
	s_mov_b32 s35, s53
	v_lshl_add_u64 v[76:77], v[76:77], 0, s[34:35]
	v_lshlrev_b32_e32 v0, 1, v162
	v_or_b32_e32 v2, 0x40000, v2
	v_lshl_add_u64 v[76:77], v[76:77], 0, v[0:1]
	s_mov_b64 s[18:19], 0x3800
	v_lshl_add_u64 v[2:3], v[8:9], 0, v[2:3]
	v_lshl_add_u64 v[78:79], v[76:77], 0, s[18:19]
	v_add_co_u32_e32 v76, vcc, 0x3000, v76
	v_lshl_add_u64 v[2:3], v[2:3], 0, s[34:35]
	s_nop 0
	v_addc_co_u32_e32 v77, vcc, 0, v77, vcc
	v_lshl_add_u64 v[2:3], v[2:3], 0, v[0:1]
	s_movk_i32 s11, 0x3000
	v_lshl_add_u64 v[106:107], v[2:3], 0, s[18:19]
	v_add_co_u32_e32 v2, vcc, s11, v2
	global_load_dwordx2 v[102:103], v[78:79], off offset:32
	global_load_dwordx2 v[96:97], v[78:79], off offset:64
	global_load_dwordx2 v[92:93], v[78:79], off offset:96
	global_load_dwordx2 v[88:89], v[78:79], off offset:128
	global_load_dwordx2 v[114:115], v[76:77], off offset:2048
	global_load_dwordx2 v[84:85], v[78:79], off offset:160
	global_load_dwordx2 v[80:81], v[78:79], off offset:192
	s_nop 0
	global_load_dwordx2 v[76:77], v[78:79], off offset:224
	v_addc_co_u32_e32 v3, vcc, 0, v3, vcc
	global_load_dwordx2 v[100:101], v[106:107], off offset:32
	global_load_dwordx2 v[94:95], v[106:107], off offset:64
	global_load_dwordx2 v[90:91], v[106:107], off offset:96
	global_load_dwordx2 v[86:87], v[106:107], off offset:128
	global_load_dwordx2 v[136:137], v[2:3], off offset:2048
	global_load_dwordx2 v[82:83], v[106:107], off offset:160
	global_load_dwordx2 v[78:79], v[106:107], off offset:192
	s_nop 0
	global_load_dwordx2 v[2:3], v[106:107], off offset:224
